# v58 + P3 assemble: lambda loads and the first row pair's 24 loads issued at the top of P3 into spare VGPRs (copied at the old load sites, drain waits removed)
# speedup vs baseline: 1.0176x; 1.0080x over previous
.LBB0_948:
	s_cmp_lt_i32 s4, 4
	s_cselect_b64 s[0:1], -1, 0
	s_cmp_gt_i32 s5, 3
	s_cselect_b64 s[2:3], -1, 0
	s_and_b64 s[0:1], s[0:1], s[2:3]
	s_andn2_b64 vcc, exec, s[0:1]
	s_cbranch_vccnz .LBB0_1031
	s_waitcnt vmcnt(0)
	v_mov_b32_e32 v84, v0
	s_ashr_i32 s0, s92, 3
	s_and_b32 s14, s92, 7
	s_mov_b32 s10, s0
	s_ashr_i32 s11, s0, 31
	s_lshl_b64 s[12:13], s[10:11], 12
	v_ashrrev_i32_e32 v230, 4, v84
	v_lshlrev_b32_e32 v236, 4, v84
	v_mov_b32_e32 v237, 0
	v_lshl_add_u32 v232, s14, 5, v230
	v_and_b32_e32 v236, 0xf0, v236
	v_ashrrev_i32_e32 v233, 31, v232
	v_lshlrev_b32_e32 v236, 1, v236
	v_lshl_add_u64 v[234:235], s[12:13], 0, v[232:233]
	v_lshlrev_b64 v[234:235], 9, v[234:235]
	v_lshl_add_u64 v[234:235], s[96:97], 0, v[234:235]
	v_lshl_add_u64 v[238:239], v[234:235], 0, v[236:237]
	s_mov_b64 s[12:13], 0x23b80000
	v_lshl_add_u64 v[240:241], v[238:239], 0, s[12:13]
	global_load_dwordx4 v[78:81], v[240:241], off nt
	global_load_dwordx4 v[74:77], v[240:241], off offset:16 nt
	s_mov_b64 s[12:13], 0x23ba0000
	v_lshl_add_u64 v[242:243], v[238:239], 0, s[12:13]
	global_load_dwordx4 v[62:65], v[242:243], off nt
	global_load_dwordx4 v[50:53], v[242:243], off offset:16 nt
	s_mov_b64 s[12:13], 0x23bc0000
	v_lshl_add_u64 v[240:241], v[238:239], 0, s[12:13]
	global_load_dwordx4 v[46:49], v[240:241], off nt
	global_load_dwordx4 v[42:45], v[240:241], off offset:16 nt
	s_mov_b64 s[12:13], 0x23be0000
	v_lshl_add_u64 v[242:243], v[238:239], 0, s[12:13]
	global_load_dwordx4 v[38:41], v[242:243], off nt
	global_load_dwordx4 v[34:37], v[242:243], off offset:16 nt
	s_mov_b64 s[12:13], 0x23c00000
	v_lshl_add_u64 v[240:241], v[238:239], 0, s[12:13]
	global_load_dwordx4 v[30:33], v[240:241], off nt
	global_load_dwordx4 v[26:29], v[240:241], off offset:16 nt
	s_mov_b64 s[12:13], 0x23c20000
	v_lshl_add_u64 v[242:243], v[238:239], 0, s[12:13]
	global_load_dwordx4 v[22:25], v[242:243], off nt
	global_load_dwordx4 v[18:21], v[242:243], off offset:16 nt
	s_mov_b64 s[12:13], 0x23c40000
	v_lshl_add_u64 v[240:241], v[238:239], 0, s[12:13]
	global_load_dwordx4 v[14:17], v[240:241], off nt
	global_load_dwordx4 v[10:13], v[240:241], off offset:16 nt
	s_mov_b64 s[12:13], 0x23c60000
	v_lshl_add_u64 v[242:243], v[238:239], 0, s[12:13]
	global_load_dwordx4 v[6:9], v[242:243], off nt
	global_load_dwordx4 v[2:5], v[242:243], off offset:16 nt
	s_mov_b64 s[12:13], 0x23c80000
	v_lshl_add_u64 v[240:241], v[238:239], 0, s[12:13]
	global_load_dwordx4 v[110:113], v[240:241], off nt
	global_load_dwordx4 v[114:117], v[240:241], off offset:16 nt
	s_mov_b64 s[12:13], 0x23ca0000
	v_lshl_add_u64 v[242:243], v[238:239], 0, s[12:13]
	global_load_dwordx4 v[118:121], v[242:243], off nt
	global_load_dwordx4 v[122:125], v[242:243], off offset:16 nt
	s_mov_b64 s[12:13], 0x23cc0000
	v_lshl_add_u64 v[240:241], v[238:239], 0, s[12:13]
	global_load_dwordx4 v[126:129], v[240:241], off nt
	global_load_dwordx4 v[130:133], v[240:241], off offset:16 nt
	s_mov_b64 s[12:13], 0x23ce0000
	v_lshl_add_u64 v[242:243], v[238:239], 0, s[12:13]
	global_load_dwordx4 v[134:137], v[242:243], off nt
	global_load_dwordx4 v[138:141], v[242:243], off offset:16 nt
	s_mov_b64 s[12:13], 0x23d00000
	v_lshl_add_u64 v[240:241], v[238:239], 0, s[12:13]
	global_load_dwordx4 v[142:145], v[240:241], off nt
	global_load_dwordx4 v[146:149], v[240:241], off offset:16 nt
	s_mov_b64 s[12:13], 0x23d20000
	v_lshl_add_u64 v[242:243], v[238:239], 0, s[12:13]
	global_load_dwordx4 v[150:153], v[242:243], off nt
	global_load_dwordx4 v[154:157], v[242:243], off offset:16 nt
	s_mov_b64 s[12:13], 0x23d40000
	v_lshl_add_u64 v[240:241], v[238:239], 0, s[12:13]
	global_load_dwordx4 v[158:161], v[240:241], off nt
	global_load_dwordx4 v[162:165], v[240:241], off offset:16 nt
	s_mov_b64 s[12:13], 0x23d60000
	v_lshl_add_u64 v[242:243], v[238:239], 0, s[12:13]
	global_load_dwordx4 v[166:169], v[242:243], off nt
	global_load_dwordx4 v[170:173], v[242:243], off offset:16 nt
	v_readlane_b32 s10, v245, 21
	v_readlane_b32 s11, v245, 22
	v_readlane_b32 s12, v245, 23
	v_readlane_b32 s13, v245, 24
	v_and_b32_e32 v230, 63, v84
	v_lshlrev_b32_e32 v231, 2, v230
	v_lshlrev_b32_e32 v232, 3, v230
	s_nop 4
	global_load_dword v106, v231, s[10:11]
	global_load_dword v107, v231, s[12:13]
	v_readlane_b32 s10, v245, 25
	v_readlane_b32 s11, v245, 26
	v_readlane_b32 s12, v245, 27
	v_readlane_b32 s13, v245, 28
	v_readlane_b32 s14, v245, 29
	v_readlane_b32 s15, v245, 30
	s_nop 4
	global_load_dword v108, v231, s[10:11]
	global_load_dword v109, v231, s[12:13]
	global_load_dwordx2 v[174:175], v232, s[14:15]
	v_readfirstlane_b32 s10, v84
	s_ashr_i32 s10, s10, 6
	s_lshl_b32 s11, s92, 3
	s_add_i32 s10, s10, s11
	s_lshl_b32 s10, s10, 1
	s_ashr_i32 s11, s10, 31
	s_lshl_b64 s[12:13], s[10:11], 11
	s_add_u32 s12, s12, 0x19000000
	s_addc_u32 s13, s13, 0
	s_add_u32 s12, s12, s96
	s_addc_u32 s13, s13, s97
	global_load_dword v176, v231, s[12:13]
	global_load_dword v177, v231, s[12:13] offset:256
	global_load_dword v178, v231, s[12:13] offset:512
	global_load_dword v179, v231, s[12:13] offset:768
	global_load_dword v180, v231, s[12:13] offset:1024
	global_load_dword v181, v231, s[12:13] offset:1280
	global_load_dword v182, v231, s[12:13] offset:1536
	global_load_dword v183, v231, s[12:13] offset:1792
	s_lshl_b64 s[14:15], s[10:11], 12
	s_add_u32 s14, s14, 0x10f00000
	s_addc_u32 s15, s15, 0
	s_add_u32 s14, s14, s96
	s_addc_u32 s15, s15, s97
	global_load_dword v184, v231, s[14:15] offset:2048
	global_load_dword v185, v231, s[14:15] offset:2304
	global_load_dword v186, v231, s[14:15] offset:2560
	global_load_dword v187, v231, s[14:15] offset:2816
	s_add_u32 s12, s12, 0x800
	s_addc_u32 s13, s13, 0
	global_load_dword v188, v231, s[12:13]
	global_load_dword v189, v231, s[12:13] offset:256
	global_load_dword v190, v231, s[12:13] offset:512
	global_load_dword v191, v231, s[12:13] offset:768
	global_load_dword v192, v231, s[12:13] offset:1024
	global_load_dword v193, v231, s[12:13] offset:1280
	global_load_dword v194, v231, s[12:13] offset:1536
	global_load_dword v195, v231, s[12:13] offset:1792
	s_add_u32 s14, s14, 0x1000
	s_addc_u32 s15, s15, 0
	global_load_dword v196, v231, s[14:15] offset:2048
	global_load_dword v197, v231, s[14:15] offset:2304
	global_load_dword v198, v231, s[14:15] offset:2560
	global_load_dword v199, v231, s[14:15] offset:2816
	s_nop 0
	v_cmp_gt_i32_e32 vcc, 32, v84
	v_lshl_add_u32 v201, v84, 2, 0
	v_lshl_add_u32 v210, s0, 5, v84
	s_and_saveexec_b64 s[2:3], vcc
	s_cbranch_execz .LBB0_951
	v_ashrrev_i32_e32 v211, 31, v210
	v_lshl_add_u64 v[202:203], v[210:211], 2, s[96:97]
	v_add_co_u32_e32 v202, vcc, 0x2bc80000, v202
	s_nop 1
	v_addc_co_u32_e32 v203, vcc, 0, v203, vcc
	global_load_dword v202, v[202:203], off
	s_waitcnt vmcnt(0)
	ds_write_b32 v201, v202 offset:256

.LBB0_958:
	s_or_b64 exec, exec, s[2:3]
	v_mov_b32_e32 v1, v0
	s_barrier
	v_readlane_b32 s0, v245, 9
	v_and_b32_e32 v13, 63, v1
	v_lshlrev_b32_e32 v6, 2, v13
	v_readlane_b32 s12, v245, 21
	v_readlane_b32 s13, v245, 22
	v_readlane_b32 s14, v245, 23
	v_readlane_b32 s15, v245, 24
	s_nop 2
	v_mov_b32_e32 v4, v106
	s_nop 0
	v_mov_b32_e32 v5, v107
	v_mov_b32_e32 v7, v108
	v_mov_b32_e32 v8, v109
	v_lshlrev_b32_e32 v2, 3, v13
	v_mov_b32_e32 v2, v174
	v_mov_b32_e32 v3, v175
	v_readlane_b32 s2, v245, 11
	s_mov_b32 s2, 0x3fb8aa3b
	v_readlane_b32 s3, v245, 12
	s_mov_b32 s3, 0xc2ce8ed0
	v_readlane_b32 s6, v245, 15
	v_readlane_b32 s1, v245, 10
	s_mov_b32 s6, 0x42b17218
	v_readfirstlane_b32 s20, v1
	s_lshl_b32 s1, s92, 3
	v_mov_b32_e32 v9, 0x7f800000
	s_ashr_i32 s0, s20, 6
	v_readlane_b32 s4, v245, 13
	s_add_i32 s33, s0, s1
	v_readlane_b32 s5, v245, 14
	s_add_u32 s4, s96, 0x10f00000
	v_lshlrev_b32_e32 v14, 1, v13
	s_addc_u32 s5, s97, 0
	s_cmpk_gt_i32 s33, 0x1fff
	v_readlane_b32 s7, v245, 16
	v_readlane_b32 s8, v245, 17
	v_readlane_b32 s9, v245, 18
	v_readlane_b32 s10, v245, 19
	v_readlane_b32 s11, v245, 20
	v_mul_f32_e32 v10, v4, v5
	s_nop 1
	v_mov_b32_dpp v10, v10 quad_perm:[1,0,3,2] row_mask:0xf bank_mask:0xf bound_ctrl:1
	v_mul_f32_e32 v11, v7, v8
	v_fmac_f32_e32 v10, v4, v5
	s_nop 0
	v_mov_b32_dpp v11, v11 quad_perm:[1,0,3,2] row_mask:0xf bank_mask:0xf bound_ctrl:1
	v_fmac_f32_e32 v11, v7, v8
	v_add_f32_dpp v4, v10, v10 quad_perm:[2,3,0,1] row_mask:0xf bank_mask:0xf bound_ctrl:1
	s_nop 0
	v_add_f32_dpp v5, v11, v11 quad_perm:[2,3,0,1] row_mask:0xf bank_mask:0xf bound_ctrl:1
	v_add_f32_dpp v4, v4, v4 row_ror:4 row_mask:0xf bank_mask:0xf bound_ctrl:1
	s_nop 0
	v_add_f32_dpp v5, v5, v5 row_ror:4 row_mask:0xf bank_mask:0xf bound_ctrl:1
	v_add_f32_dpp v4, v4, v4 row_ror:8 row_mask:0xf bank_mask:0xf bound_ctrl:1
	v_mov_b32_e32 v7, v4
	v_add_f32_dpp v5, v5, v5 row_ror:8 row_mask:0xf bank_mask:0xf bound_ctrl:1
	v_mov_b32_e32 v8, v5
	v_permlane16_swap_b32_e32 v4, v7
	s_nop 0
	v_permlane16_swap_b32_e32 v5, v8
	v_add_f32_e32 v4, v4, v7
	v_add_f32_e32 v5, v5, v8
	v_mov_b32_e32 v7, v4
	v_mov_b32_e32 v8, v5
	s_nop 0
	v_permlane32_swap_b32_e32 v4, v7
	v_permlane32_swap_b32_e32 v5, v8
	v_add_f32_e32 v4, v4, v7
	v_add_f32_e32 v5, v5, v8
	v_mul_f32_e32 v7, 0x3fb8aa3b, v4
	v_mul_f32_e32 v8, 0x3fb8aa3b, v5
	v_fma_f32 v10, v4, s2, -v7
	v_rndne_f32_e32 v11, v7
	v_fma_f32 v12, v5, s2, -v8
	v_rndne_f32_e32 v15, v8
	v_fmac_f32_e32 v10, 0x32a5705f, v4
	v_sub_f32_e32 v7, v7, v11
	v_fmac_f32_e32 v12, 0x32a5705f, v5
	v_sub_f32_e32 v8, v8, v15
	v_add_f32_e32 v7, v7, v10
	v_cvt_i32_f32_e32 v11, v11
	v_add_f32_e32 v8, v8, v12
	v_exp_f32_e32 v7, v7
	v_cvt_i32_f32_e32 v15, v15
	v_exp_f32_e32 v8, v8
	v_cmp_ngt_f32_e32 vcc, s3, v4
	v_ldexp_f32 v7, v7, v11
	v_ldexp_f32 v8, v8, v15
	v_cndmask_b32_e32 v7, 0, v7, vcc
	v_cmp_ngt_f32_e32 vcc, s3, v5
	s_nop 1
	v_cndmask_b32_e32 v8, 0, v8, vcc
	v_cmp_nlt_f32_e32 vcc, s6, v4
	s_nop 1
	v_cndmask_b32_e32 v4, v9, v7, vcc
	v_cmp_nlt_f32_e32 vcc, s6, v5
	s_nop 1
	v_cndmask_b32_e32 v5, v9, v8, vcc
	v_sub_f32_e32 v4, v4, v5
	v_add_f32_e32 v4, 0x3e4ccccd, v4
	v_lshlrev_b32_e32 v8, 1, v14
	s_cbranch_scc1 .LBB0_963
	s_add_u32 s1, s96, 0x19000000
	s_addc_u32 s14, s97, 0
	s_lshl_b32 s2, s33, 1
	s_ashr_i32 s3, s2, 31
	s_lshl_b64 s[6:7], s[2:3], 11
	s_add_u32 s6, s1, s6
	s_addc_u32 s7, s14, s7
	s_lshl_b64 s[8:9], s[2:3], 12
	s_add_u32 s10, s4, s8
	s_addc_u32 s11, s5, s9
	v_mov_b32_e32 v11, v176
	v_mov_b32_e32 v10, v177
	v_mov_b32_e32 v59, v178
	v_mov_b32_e32 v58, v179
	v_mov_b32_e32 v56, v180
	v_mov_b32_e32 v55, v181
	v_mov_b32_e32 v53, v182
	v_mov_b32_e32 v52, v183
	s_or_b32 s6, s2, 1
	s_mov_b32 s7, s3
	s_lshl_b64 s[12:13], s[6:7], 11
	s_add_u32 s12, s1, s12
	s_addc_u32 s13, s14, s13
	s_lshl_b64 s[6:7], s[6:7], 12
	s_add_u32 s6, s4, s6
	v_mov_b32_e32 v60, v184
	v_mov_b32_e32 v57, v185
	v_mov_b32_e32 v54, v186
	v_mov_b32_e32 v50, v187
	v_mov_b32_e32 v51, v188
	v_mov_b32_e32 v49, v189
	v_mov_b32_e32 v47, v190
	v_mov_b32_e32 v46, v191
	v_mov_b32_e32 v43, v193
	s_addc_u32 s7, s5, s7
	v_mov_b32_e32 v44, v192
	v_mov_b32_e32 v48, v196
	v_mov_b32_e32 v45, v197
	v_mov_b32_e32 v25, v198
	v_mov_b32_e32 v15, v199
	v_mov_b32_e32 v22, v195
	v_mov_b32_e32 v26, v194
	s_lshl_b32 s6, s95, 4
	s_add_u32 s8, s96, s8
	s_addc_u32 s9, s97, s9
	s_lshl_b32 s1, s92, 4
	s_lshl_b32 s0, s0, 1
	s_add_i32 s1, s1, s6
	s_add_i32 s0, s1, s0
	s_ashr_i32 s7, s6, 31
	s_ashr_i32 s1, s0, 31
	s_lshl_b64 s[10:11], s[6:7], 12
	s_lshl_b64 s[12:13], s[0:1], 12
	s_add_u32 s12, s96, s12
	s_addc_u32 s13, s97, s13
	s_lshl_b64 s[0:1], s[0:1], 11
	s_add_u32 s14, s96, s0
	v_mov_b32_e32 v5, v4
	v_mov_b32_e32 v7, 0
	v_mov_b32_e32 v9, 0x3727c5ac
	s_mov_b32 s3, 0xf800000
	v_mov_b32_e32 v12, 0x260
	s_mov_b32 s21, 0x3f4ccccd
	s_mov_b32 s22, 0x1b000000
	s_mov_b32 s23, 0x1b001000
	s_addc_u32 s15, s97, s1
	s_lshl_b64 s[16:17], s[6:7], 11
	v_mov_b32_e32 v18, v11
	v_mov_b32_e32 v16, v10
	v_mov_b32_e32 v20, v59
	v_mov_b32_e32 v17, v58
	v_mov_b32_e32 v23, v56
	v_mov_b32_e32 v19, v55
	v_mov_b32_e32 v24, v53
	v_mov_b32_e32 v21, v52
	v_mov_b32_e32 v30, v60
	v_mov_b32_e32 v32, v57
	v_mov_b32_e32 v34, v54
	v_mov_b32_e32 v36, v50
	v_mov_b32_e32 v27, v49
	v_mov_b32_e32 v28, v51
	v_mov_b32_e32 v29, v46
	v_mov_b32_e32 v33, v43
	v_mov_b32_e32 v31, v47
	v_mov_b32_e32 v35, v44
	v_mov_b32_e32 v39, v48
	v_mov_b32_e32 v40, v45
	v_mov_b32_e32 v41, v25
	v_mov_b32_e32 v42, v15
	v_mov_b32_e32 v37, v22
	v_mov_b32_e32 v38, v26
	s_branch .LBB0_961
